# window edge tiles: own one-sided band mask + interleaved softmax (old compiler masked-tile code removed)
# speedup vs baseline: 1.0128x; 1.0011x over previous
; #define ATT_LAS __attribute__((address_space(3)))
; __device__ __forceinline__ int crow(int r, int hi) { return (r & 3) + 8 * (r >> 2) + 4 * hi; }
; __device__ __forceinline__ void attn_unit(int uv, const float* sink_l, const bf16_t* P, bf16_t* Y, ATT_LAS unsigned char* lds, const float* rpb_l, const float* qn_l, const float* kn_l) {
;     ...
;                 const ATT_LAS unsigned char* Kb = ATT_KBUF(cur); const ATT_LAS unsigned char* Vb = ATT_VBUF(cur);
;                 f32x16 p0 = {}, p1 = {};
; #pragma unroll
;                 for (int d0 = 0; d0 < 4; ++d0) {
;                     const bf16x8 k0 = *(const ATT_LAS bf16x8*)(Kb + kfrag + d0 * 2048);
;                     const bf16x8 k1 = *(const ATT_LAS bf16x8*)(Kb + kfrag + d0 * 2048 + 512);
;                     p0 = __builtin_amdgcn_mfma_f32_32x32x16_bf16(k0, qf[d0], p0, 0, 0, 0);
;                     p1 = __builtin_amdgcn_mfma_f32_32x32x16_bf16(k1, qf[d0], p1, 0, 0, 0);
;                 }
;                 if (a.mode == 1) { const int dq = tl * 64 - (qw + r32);
; #pragma unroll
;                     for (int r = 0; r < 16; ++r) { const int d = dq + crow(r, hi); if (d > 128 || d < -128) p0[r] = NEGF; if (d + 32 > 128 || d + 32 < -128) p1[r] = NEGF; } }
.Lmsk_win_edge:
	ds_read_b64_tr_b16 v[160:161], v242 offset:24576
	ds_read_b64_tr_b16 v[162:163], v242 offset:25088
	ds_read_b64_tr_b16 v[176:177], v242 offset:28672
	ds_read_b64_tr_b16 v[178:179], v242 offset:29184
	ds_read_b64_tr_b16 v[164:165], v242 offset:25600
	ds_read_b64_tr_b16 v[166:167], v242 offset:26112
	ds_read_b64_tr_b16 v[180:181], v242 offset:29696
	s_waitcnt lgkmcnt(14)
	v_mfma_f32_32x32x16_bf16 v[80:95], v[128:131], v[96:99], 0
	ds_read_b64_tr_b16 v[182:183], v242 offset:30208
	s_waitcnt lgkmcnt(14)
	v_mfma_f32_32x32x16_bf16 v[48:63], v[132:135], v[96:99], 0
	ds_read_b64_tr_b16 v[168:169], v242 offset:26624
	s_waitcnt lgkmcnt(14)
	v_mfma_f32_32x32x16_bf16 v[80:95], v[136:139], v[100:103], v[80:95]
	ds_read_b64_tr_b16 v[170:171], v242 offset:27136
	s_waitcnt lgkmcnt(14)
	v_mfma_f32_32x32x16_bf16 v[48:63], v[140:143], v[100:103], v[48:63]
	ds_read_b64_tr_b16 v[184:185], v242 offset:30720
	s_waitcnt lgkmcnt(14)
	v_mfma_f32_32x32x16_bf16 v[80:95], v[144:147], v[104:107], v[80:95]
	ds_read_b64_tr_b16 v[186:187], v242 offset:31232
	s_waitcnt lgkmcnt(14)
	v_mfma_f32_32x32x16_bf16 v[48:63], v[148:151], v[104:107], v[48:63]
	ds_read_b64_tr_b16 v[172:173], v242 offset:27648
	s_waitcnt lgkmcnt(14)
	v_mfma_f32_32x32x16_bf16 v[80:95], v[152:155], v[108:111], v[80:95]
	ds_read_b64_tr_b16 v[174:175], v242 offset:28160
	s_waitcnt lgkmcnt(14)
	v_mfma_f32_32x32x16_bf16 v[48:63], v[156:159], v[108:111], v[48:63]
	ds_read_b64_tr_b16 v[188:189], v242 offset:31744
	s_waitcnt lgkmcnt(14)
	ds_read_b64_tr_b16 v[190:191], v242 offset:32256
	v_add_u32_e32 v243, s92, v126
	s_add_i32 s72, s33, 31
	s_cmp_ge_i32 s92, s72
	s_cbranch_scc1 .Lwe_high
	v_sub_u32_e32 v243, 0xffffff80, v243
	s_nop 3
	v_cmp_le_i32_e64 s[8:9], v243, 0
	v_cmp_le_i32_e64 s[10:11], v243, 1
	v_cmp_le_i32_e64 s[12:13], v243, 2
	v_cmp_le_i32_e64 s[14:15], v243, 3
	v_cndmask_b32_e64 v80, v216, v80, s[8:9]
	v_cndmask_b32_e64 v81, v216, v81, s[10:11]
	v_cndmask_b32_e64 v82, v216, v82, s[12:13]
	v_cndmask_b32_e64 v83, v216, v83, s[14:15]
	v_cmp_le_i32_e64 s[8:9], v243, 8
	v_cmp_le_i32_e64 s[10:11], v243, 9
	v_cmp_le_i32_e64 s[12:13], v243, 10
	v_cmp_le_i32_e64 s[14:15], v243, 11
	v_cndmask_b32_e64 v84, v216, v84, s[8:9]
	v_cndmask_b32_e64 v85, v216, v85, s[10:11]
	v_cndmask_b32_e64 v86, v216, v86, s[12:13]
	v_cndmask_b32_e64 v87, v216, v87, s[14:15]
	v_cmp_le_i32_e64 s[8:9], v243, 16
	v_cmp_le_i32_e64 s[10:11], v243, 17
	v_cmp_le_i32_e64 s[12:13], v243, 18
	v_cmp_le_i32_e64 s[14:15], v243, 19
	v_cndmask_b32_e64 v88, v216, v88, s[8:9]
	v_cndmask_b32_e64 v89, v216, v89, s[10:11]
	v_cndmask_b32_e64 v90, v216, v90, s[12:13]
	v_cndmask_b32_e64 v91, v216, v91, s[14:15]
	v_cmp_le_i32_e64 s[8:9], v243, 24
	v_cmp_le_i32_e64 s[10:11], v243, 25
	v_cmp_le_i32_e64 s[12:13], v243, 26
	v_cmp_le_i32_e64 s[14:15], v243, 27
	v_cndmask_b32_e64 v92, v216, v92, s[8:9]
	v_cndmask_b32_e64 v93, v216, v93, s[10:11]
	v_cndmask_b32_e64 v94, v216, v94, s[12:13]
	v_cndmask_b32_e64 v95, v216, v95, s[14:15]
	v_cmp_le_i32_e64 s[8:9], v243, 32
	v_cmp_le_i32_e64 s[10:11], v243, 33
	v_cmp_le_i32_e64 s[12:13], v243, 34
	v_cmp_le_i32_e64 s[14:15], v243, 35
	v_cndmask_b32_e64 v48, v216, v48, s[8:9]
	v_cndmask_b32_e64 v49, v216, v49, s[10:11]
	v_cndmask_b32_e64 v50, v216, v50, s[12:13]
	v_cndmask_b32_e64 v51, v216, v51, s[14:15]
	v_cmp_le_i32_e64 s[8:9], v243, 40
	v_cmp_le_i32_e64 s[10:11], v243, 41
	v_cmp_le_i32_e64 s[12:13], v243, 42
	v_cmp_le_i32_e64 s[14:15], v243, 43
	v_cndmask_b32_e64 v52, v216, v52, s[8:9]
	v_cndmask_b32_e64 v53, v216, v53, s[10:11]
	v_cndmask_b32_e64 v54, v216, v54, s[12:13]
	v_cndmask_b32_e64 v55, v216, v55, s[14:15]
	v_cmp_le_i32_e64 s[8:9], v243, 48
	v_cmp_le_i32_e64 s[10:11], v243, 49
	v_cmp_le_i32_e64 s[12:13], v243, 50
	v_cmp_le_i32_e64 s[14:15], v243, 51
	v_cndmask_b32_e64 v56, v216, v56, s[8:9]
	v_cndmask_b32_e64 v57, v216, v57, s[10:11]
	v_cndmask_b32_e64 v58, v216, v58, s[12:13]
	v_cndmask_b32_e64 v59, v216, v59, s[14:15]
	v_cmp_le_i32_e64 s[8:9], v243, 56
	v_cmp_le_i32_e64 s[10:11], v243, 57
	v_cmp_le_i32_e64 s[12:13], v243, 58
	v_cmp_le_i32_e64 s[14:15], v243, 59
	v_cndmask_b32_e64 v60, v216, v60, s[8:9]
	v_cndmask_b32_e64 v61, v216, v61, s[10:11]
	v_cndmask_b32_e64 v62, v216, v62, s[12:13]
	v_cndmask_b32_e64 v63, v216, v63, s[14:15]
	s_branch .Lwe_soft
.Lwe_high:
	v_sub_u32_e32 v243, 0x80, v243
	s_nop 3
	v_cmp_ge_i32_e64 s[8:9], v243, 0
	v_cmp_ge_i32_e64 s[10:11], v243, 1
	v_cmp_ge_i32_e64 s[12:13], v243, 2
	v_cmp_ge_i32_e64 s[14:15], v243, 3
	v_cndmask_b32_e64 v80, v216, v80, s[8:9]
	v_cndmask_b32_e64 v81, v216, v81, s[10:11]
	v_cndmask_b32_e64 v82, v216, v82, s[12:13]
	v_cndmask_b32_e64 v83, v216, v83, s[14:15]
	v_cmp_ge_i32_e64 s[8:9], v243, 8
	v_cmp_ge_i32_e64 s[10:11], v243, 9
	v_cmp_ge_i32_e64 s[12:13], v243, 10
	v_cmp_ge_i32_e64 s[14:15], v243, 11
	v_cndmask_b32_e64 v84, v216, v84, s[8:9]
	v_cndmask_b32_e64 v85, v216, v85, s[10:11]
	v_cndmask_b32_e64 v86, v216, v86, s[12:13]
	v_cndmask_b32_e64 v87, v216, v87, s[14:15]
	v_cmp_ge_i32_e64 s[8:9], v243, 16
	v_cmp_ge_i32_e64 s[10:11], v243, 17
	v_cmp_ge_i32_e64 s[12:13], v243, 18
	v_cmp_ge_i32_e64 s[14:15], v243, 19
	v_cndmask_b32_e64 v88, v216, v88, s[8:9]
	v_cndmask_b32_e64 v89, v216, v89, s[10:11]
	v_cndmask_b32_e64 v90, v216, v90, s[12:13]
	v_cndmask_b32_e64 v91, v216, v91, s[14:15]
	v_cmp_ge_i32_e64 s[8:9], v243, 24
	v_cmp_ge_i32_e64 s[10:11], v243, 25
	v_cmp_ge_i32_e64 s[12:13], v243, 26
	v_cmp_ge_i32_e64 s[14:15], v243, 27
	v_cndmask_b32_e64 v92, v216, v92, s[8:9]
	v_cndmask_b32_e64 v93, v216, v93, s[10:11]
	v_cndmask_b32_e64 v94, v216, v94, s[12:13]
	v_cndmask_b32_e64 v95, v216, v95, s[14:15]
	v_cmp_ge_i32_e64 s[8:9], v243, 32
	v_cmp_ge_i32_e64 s[10:11], v243, 33
	v_cmp_ge_i32_e64 s[12:13], v243, 34
	v_cmp_ge_i32_e64 s[14:15], v243, 35
	v_cndmask_b32_e64 v48, v216, v48, s[8:9]
	v_cndmask_b32_e64 v49, v216, v49, s[10:11]
	v_cndmask_b32_e64 v50, v216, v50, s[12:13]
	v_cndmask_b32_e64 v51, v216, v51, s[14:15]
	v_cmp_ge_i32_e64 s[8:9], v243, 40
	v_cmp_ge_i32_e64 s[10:11], v243, 41
	v_cmp_ge_i32_e64 s[12:13], v243, 42
	v_cmp_ge_i32_e64 s[14:15], v243, 43
	v_cndmask_b32_e64 v52, v216, v52, s[8:9]
	v_cndmask_b32_e64 v53, v216, v53, s[10:11]
	v_cndmask_b32_e64 v54, v216, v54, s[12:13]
	v_cndmask_b32_e64 v55, v216, v55, s[14:15]
	v_cmp_ge_i32_e64 s[8:9], v243, 48
	v_cmp_ge_i32_e64 s[10:11], v243, 49
	v_cmp_ge_i32_e64 s[12:13], v243, 50
	v_cmp_ge_i32_e64 s[14:15], v243, 51
	v_cndmask_b32_e64 v56, v216, v56, s[8:9]
	v_cndmask_b32_e64 v57, v216, v57, s[10:11]
	v_cndmask_b32_e64 v58, v216, v58, s[12:13]
	v_cndmask_b32_e64 v59, v216, v59, s[14:15]
	v_cmp_ge_i32_e64 s[8:9], v243, 56
	v_cmp_ge_i32_e64 s[10:11], v243, 57
	v_cmp_ge_i32_e64 s[12:13], v243, 58
	v_cmp_ge_i32_e64 s[14:15], v243, 59
	v_cndmask_b32_e64 v60, v216, v60, s[8:9]
	v_cndmask_b32_e64 v61, v216, v61, s[10:11]
	v_cndmask_b32_e64 v62, v216, v62, s[12:13]
	v_cndmask_b32_e64 v63, v216, v63, s[14:15]
; #define ATT_LAS __attribute__((address_space(3)))
; __device__ __forceinline__ unsigned pk_bf16(float lo, float hi) { unsigned r; asm volatile("v_cvt_pk_bf16_f32 %0, %1, %2" : "=v"(r) : "v"(lo), "v"(hi)); return r; }
; __device__ __forceinline__ void attn_unit(int uv, const float* sink_l, const bf16_t* P, bf16_t* Y, ATT_LAS unsigned char* lds, const float* rpb_l, const float* qn_l, const float* kn_l) {
;     ...
;                 const float mt = rowmax32(p0, p1);
;                 if (__any(mt > m)) { const float mn = fmaxf(m, mt), alpha = __builtin_amdgcn_exp2f(m - mn); m = mn; lsum *= alpha;
; #pragma unroll
;                     for (int r = 0; r < 16; ++r) { o0[r] *= alpha; o1[r] *= alpha; } }
;                 float sum = 0.f;
; #pragma unroll
;                 for (int r = 0; r < 16; ++r) { p0[r] = __builtin_amdgcn_exp2f(p0[r] - m); p1[r] = __builtin_amdgcn_exp2f(p1[r] - m); sum += p0[r] + p1[r]; }
;                 lsum += sum;
;                 u32x4 pw[4];
; #pragma unroll
;                 for (int j = 0; j < 4; ++j) { pw[0][j] = pk_bf16(p0[2 * j], p0[2 * j + 1]); pw[1][j] = pk_bf16(p0[8 + 2 * j], p0[8 + 2 * j + 1]);
;                                               pw[2][j] = pk_bf16(p1[2 * j], p1[2 * j + 1]); pw[3][j] = pk_bf16(p1[8 + 2 * j], p1[8 + 2 * j + 1]); }
;                 const ATT_LAS unsigned char* vb = Vb + vlane;
; #pragma unroll
;                 for (int s = 0; s < 4; ++s) {
;                     const bf16x8 pa = __builtin_bit_cast(bf16x8, pw[s]);
;                     { const s16x4 lo = vtr(vb + s * 1024), h4 = vtr(vb + s * 1024 + 512);
;                       const bf16x8 vf = (bf16x8){lo[0], lo[1], lo[2], lo[3], h4[0], h4[1], h4[2], h4[3]};
;                       o0 = __builtin_amdgcn_mfma_f32_32x32x16_bf16(vf, pa, o0, 0, 0, 0); }
;                     { const s16x4 lo = vtr(vb + 4096 + s * 1024), h4 = vtr(vb + 4096 + s * 1024 + 512);
;                       const bf16x8 vf = (bf16x8){lo[0], lo[1], lo[2], lo[3], h4[0], h4[1], h4[2], h4[3]};
;                       o1 = __builtin_amdgcn_mfma_f32_32x32x16_bf16(vf, pa, o1, 0, 0, 0); }
;                 }
.Lwe_soft:
	v_max3_f32 v204, v80, v84, v88
	v_max3_f32 v205, v81, v85, v89
	v_max3_f32 v208, v82, v86, v90
	v_max3_f32 v209, v83, v87, v91
	v_max3_f32 v204, v204, v92, v48
	v_max3_f32 v205, v205, v93, v49
	v_max3_f32 v208, v208, v94, v50
	v_max3_f32 v209, v209, v95, v51
	v_max3_f32 v204, v204, v52, v56
	v_max3_f32 v205, v205, v53, v57
	v_max3_f32 v208, v208, v54, v58
	v_max3_f32 v209, v209, v55, v59
	v_max_f32_e32 v204, v204, v60
	v_max_f32_e32 v205, v205, v61
	v_max_f32_e32 v208, v208, v62
	v_max_f32_e32 v209, v209, v63
	v_max3_f32 v204, v204, v205, v208
	v_max_f32_e32 v204, v204, v209
	v_mov_b32_e32 v205, v204
	s_nop 1
	v_permlane32_swap_b32_e32 v204, v205
	v_max_f32_e32 v204, v204, v205
	v_cmp_gt_f32_e32 vcc, v204, v202
	s_cbranch_vccz .Lnb_we_norescale
	v_max_f32_e32 v205, v202, v204
	v_sub_f32_e32 v208, v202, v205
	v_exp_f32_e32 v208, v208
	v_mov_b32_e32 v202, v205
	v_pk_mul_f32 v[0:1], v[0:1], v[208:209] op_sel_hi:[1,0]
	v_pk_mul_f32 v[2:3], v[2:3], v[208:209] op_sel_hi:[1,0]
	v_pk_mul_f32 v[4:5], v[4:5], v[208:209] op_sel_hi:[1,0]
	v_pk_mul_f32 v[6:7], v[6:7], v[208:209] op_sel_hi:[1,0]
	v_pk_mul_f32 v[8:9], v[8:9], v[208:209] op_sel_hi:[1,0]
	v_pk_mul_f32 v[10:11], v[10:11], v[208:209] op_sel_hi:[1,0]
	v_pk_mul_f32 v[12:13], v[12:13], v[208:209] op_sel_hi:[1,0]
	v_pk_mul_f32 v[14:15], v[14:15], v[208:209] op_sel_hi:[1,0]
	v_pk_mul_f32 v[16:17], v[16:17], v[208:209] op_sel_hi:[1,0]
	v_pk_mul_f32 v[18:19], v[18:19], v[208:209] op_sel_hi:[1,0]
	v_pk_mul_f32 v[20:21], v[20:21], v[208:209] op_sel_hi:[1,0]
	v_pk_mul_f32 v[22:23], v[22:23], v[208:209] op_sel_hi:[1,0]
	v_pk_mul_f32 v[24:25], v[24:25], v[208:209] op_sel_hi:[1,0]
	v_pk_mul_f32 v[26:27], v[26:27], v[208:209] op_sel_hi:[1,0]
	v_pk_mul_f32 v[28:29], v[28:29], v[208:209] op_sel_hi:[1,0]
	v_pk_mul_f32 v[30:31], v[30:31], v[208:209] op_sel_hi:[1,0]
	v_mul_f32_e32 v124, v124, v208
.Lnb_we_norescale:
	v_sub_f32_e32 v80, v80, v202
	v_sub_f32_e32 v81, v81, v202
	v_sub_f32_e32 v82, v82, v202
	v_sub_f32_e32 v83, v83, v202
	v_sub_f32_e32 v84, v84, v202
	v_sub_f32_e32 v85, v85, v202
	v_sub_f32_e32 v86, v86, v202
	v_sub_f32_e32 v87, v87, v202
	v_sub_f32_e32 v88, v88, v202
	v_sub_f32_e32 v89, v89, v202
	v_sub_f32_e32 v90, v90, v202
	v_sub_f32_e32 v91, v91, v202
	v_sub_f32_e32 v92, v92, v202
	v_sub_f32_e32 v93, v93, v202
	v_sub_f32_e32 v94, v94, v202
	v_sub_f32_e32 v95, v95, v202
	v_sub_f32_e32 v48, v48, v202
	v_sub_f32_e32 v49, v49, v202
	v_sub_f32_e32 v50, v50, v202
	v_sub_f32_e32 v51, v51, v202
	v_sub_f32_e32 v52, v52, v202
	v_sub_f32_e32 v53, v53, v202
	v_sub_f32_e32 v54, v54, v202
	v_sub_f32_e32 v55, v55, v202
	v_sub_f32_e32 v56, v56, v202
	v_sub_f32_e32 v57, v57, v202
	v_sub_f32_e32 v58, v58, v202
	v_sub_f32_e32 v59, v59, v202
	v_sub_f32_e32 v60, v60, v202
	v_sub_f32_e32 v61, v61, v202
	v_sub_f32_e32 v62, v62, v202
	v_sub_f32_e32 v63, v63, v202
	v_exp_f32_e32 v80, v80
	v_exp_f32_e32 v81, v81
	v_exp_f32_e32 v82, v82
	v_exp_f32_e32 v83, v83
	v_exp_f32_e32 v84, v84
	v_exp_f32_e32 v85, v85
	v_exp_f32_e32 v86, v86
	v_exp_f32_e32 v87, v87
	v_exp_f32_e32 v88, v88
	v_exp_f32_e32 v89, v89
	v_exp_f32_e32 v90, v90
	v_exp_f32_e32 v91, v91
	v_exp_f32_e32 v92, v92
	v_exp_f32_e32 v93, v93
	v_exp_f32_e32 v94, v94
	v_exp_f32_e32 v95, v95
	v_exp_f32_e32 v48, v48
	v_exp_f32_e32 v49, v49
	v_exp_f32_e32 v50, v50
	v_exp_f32_e32 v51, v51
	v_exp_f32_e32 v52, v52
	v_exp_f32_e32 v53, v53
	v_exp_f32_e32 v54, v54
	v_exp_f32_e32 v55, v55
	v_exp_f32_e32 v56, v56
	v_exp_f32_e32 v57, v57
	v_exp_f32_e32 v58, v58
	v_exp_f32_e32 v59, v59
	v_exp_f32_e32 v60, v60
	v_exp_f32_e32 v61, v61
	v_exp_f32_e32 v62, v62
	v_exp_f32_e32 v63, v63
	v_cvt_pk_bf16_f32 v32, v80, v81
	v_cvt_pk_bf16_f32 v33, v82, v83
	v_cvt_pk_bf16_f32 v34, v84, v85
	v_cvt_pk_bf16_f32 v35, v86, v87
	v_cvt_pk_bf16_f32 v36, v88, v89
	v_cvt_pk_bf16_f32 v37, v90, v91
	v_cvt_pk_bf16_f32 v38, v92, v93
	v_cvt_pk_bf16_f32 v39, v94, v95
	s_nop 1
	s_waitcnt lgkmcnt(0)
	v_mfma_f32_32x32x16_bf16 v[0:15], v[160:163], v[32:35], v[0:15]
	v_cvt_pk_bf16_f32 v40, v48, v49
	v_cvt_pk_bf16_f32 v41, v50, v51
	v_cvt_pk_bf16_f32 v42, v52, v53
	v_cvt_pk_bf16_f32 v43, v54, v55
	v_mfma_f32_32x32x16_bf16 v[16:31], v[176:179], v[32:35], v[16:31]
	v_mov_b32_e32 v204, v80
	v_mov_b32_e32 v205, v81
	v_mov_b32_e32 v208, v82
	v_mov_b32_e32 v209, v83
	v_add_f32_e32 v204, v204, v84
	v_add_f32_e32 v205, v205, v85
	v_add_f32_e32 v208, v208, v86
	v_add_f32_e32 v209, v209, v87
	v_add_f32_e32 v204, v204, v88
	v_mfma_f32_32x32x16_bf16 v[0:15], v[164:167], v[36:39], v[0:15]
	v_cvt_pk_bf16_f32 v44, v56, v57
	v_cvt_pk_bf16_f32 v45, v58, v59
	v_cvt_pk_bf16_f32 v46, v60, v61
	v_cvt_pk_bf16_f32 v47, v62, v63
	v_mfma_f32_32x32x16_bf16 v[16:31], v[180:183], v[36:39], v[16:31]
	v_add_f32_e32 v205, v205, v89
	v_add_f32_e32 v208, v208, v90
	v_add_f32_e32 v209, v209, v91
	v_add_f32_e32 v204, v204, v92
	v_add_f32_e32 v205, v205, v93
	v_add_f32_e32 v208, v208, v94
	v_add_f32_e32 v209, v209, v95
	v_add_f32_e32 v204, v204, v48
	v_add_f32_e32 v205, v205, v49
	v_mfma_f32_32x32x16_bf16 v[0:15], v[168:171], v[40:43], v[0:15]
	v_mfma_f32_32x32x16_bf16 v[16:31], v[184:187], v[40:43], v[16:31]
	v_add_f32_e32 v208, v208, v50
	v_add_f32_e32 v209, v209, v51
	v_add_f32_e32 v204, v204, v52
	v_add_f32_e32 v205, v205, v53
	v_add_f32_e32 v208, v208, v54
	v_add_f32_e32 v209, v209, v55
	v_add_f32_e32 v204, v204, v56
	v_add_f32_e32 v205, v205, v57
	v_add_f32_e32 v208, v208, v58
	v_mfma_f32_32x32x16_bf16 v[0:15], v[172:175], v[44:47], v[0:15]
	v_mfma_f32_32x32x16_bf16 v[16:31], v[188:191], v[44:47], v[16:31]
	v_add_f32_e32 v209, v209, v59
	v_add_f32_e32 v204, v204, v60
	v_add_f32_e32 v205, v205, v61
	v_add_f32_e32 v208, v208, v62
	v_add_f32_e32 v209, v209, v63
	v_add_f32_e32 v204, v204, v205
	v_add_f32_e32 v208, v208, v209
	v_add_f32_e32 v204, v204, v208
	v_add_f32_e32 v124, v124, v204
	s_branch .Lmsk_tail
.Lmsk_tail:
	s_add_i32 s92, s92, 64
	v_add_u32_e32 v127, 0x7c, v127
	s_add_i32 s7, s7, 1
	s_add_i32 s32, s32, 1
	s_cmp_eq_u32 s32, 3
	s_cselect_b32 s32, 0, s32
	s_and_b64 vcc, exec, s[82:83]
	s_cbranch_vccz .Lmk_w0
	s_waitcnt vmcnt(2)
	s_branch .Lmk_w1
